# rg3 output-norm tail batched over 4 rows; hytrans rewritten with all tile loads in flight and batched row norms (same LDS image)
# baseline (speedup 1.0000x reference)
.LBB0_833:
	s_waitcnt lgkmcnt(0)
	s_barrier
	s_load_dwordx2 s[0:1], s[64:65], 0xc0
	v_lshlrev_b32_e32 v11, 2, v112
	v_xor_b32_e32 v4, 0x80, v11
	v_xor_b32_e32 v5, 64, v11
	v_xor_b32_e32 v6, 32, v11
	v_xor_b32_e32 v7, 16, v11
	v_xor_b32_e32 v8, 8, v11
	v_xor_b32_e32 v9, 4, v11
	s_lshl_b64 s[4:5], s[58:59], 2
	s_lshl_b32 s28, s13, 12
	s_add_i32 s28, s28, 0x10c00
	v_lshl_add_u32 v10, v112, 4, s28
	ds_read_b128 v[156:159], v10
	ds_read_b128 v[160:163], v10 offset:1024
	ds_read_b128 v[164:167], v10 offset:2048
	ds_read_b128 v[168:171], v10 offset:3072
	s_lshl_b32 s29, s13, 2
	s_add_i32 s29, s11, s29
	s_lshl_b32 s29, s29, 11
	s_add_u32 s29, s29, 0x21b2000
	s_add_u32 s40, s62, s29
	s_addc_u32 s41, s63, 0
	v_lshlrev_b32_e32 v0, 5, v112
	v_lshlrev_b32_e32 v1, 4, v112
	v_mov_b32_e32 v2, 0x358637bd
	s_waitcnt lgkmcnt(0)
	s_add_u32 s0, s0, s4
	s_addc_u32 s1, s1, s5
	global_load_dwordx4 v[16:19], v0, s[0:1]
	global_load_dwordx4 v[12:15], v0, s[0:1] offset:16
	v_lshlrev_b32_e32 v182, 16, v156
	v_and_b32_e32 v183, 0xffff0000, v156
	v_lshlrev_b32_e32 v184, 16, v157
	v_and_b32_e32 v185, 0xffff0000, v157
	v_lshlrev_b32_e32 v186, 16, v158
	v_and_b32_e32 v187, 0xffff0000, v158
	v_lshlrev_b32_e32 v188, 16, v159
	v_and_b32_e32 v189, 0xffff0000, v159
	v_mul_f32_e32 v20, v183, v183
	v_fmac_f32_e32 v20, v182, v182
	v_fmac_f32_e32 v20, v184, v184
	v_fmac_f32_e32 v20, v185, v185
	v_mul_f32_e32 v3, v186, v186
	v_add_f32_e32 v20, v3, v20
	v_mul_f32_e32 v3, v187, v187
	v_add_f32_e32 v20, v3, v20
	v_mul_f32_e32 v3, v188, v188
	v_add_f32_e32 v20, v3, v20
	v_mul_f32_e32 v3, v189, v189
	v_add_f32_e32 v20, v3, v20
	v_lshlrev_b32_e32 v182, 16, v160
	v_and_b32_e32 v183, 0xffff0000, v160
	v_lshlrev_b32_e32 v184, 16, v161
	v_and_b32_e32 v185, 0xffff0000, v161
	v_lshlrev_b32_e32 v186, 16, v162
	v_and_b32_e32 v187, 0xffff0000, v162
	v_lshlrev_b32_e32 v188, 16, v163
	v_and_b32_e32 v189, 0xffff0000, v163
	v_mul_f32_e32 v21, v183, v183
	v_fmac_f32_e32 v21, v182, v182
	v_fmac_f32_e32 v21, v184, v184
	v_fmac_f32_e32 v21, v185, v185
	v_mul_f32_e32 v3, v186, v186
	v_add_f32_e32 v21, v3, v21
	v_mul_f32_e32 v3, v187, v187
	v_add_f32_e32 v21, v3, v21
	v_mul_f32_e32 v3, v188, v188
	v_add_f32_e32 v21, v3, v21
	v_mul_f32_e32 v3, v189, v189
	v_add_f32_e32 v21, v3, v21
	v_lshlrev_b32_e32 v182, 16, v164
	v_and_b32_e32 v183, 0xffff0000, v164
	v_lshlrev_b32_e32 v184, 16, v165
	v_and_b32_e32 v185, 0xffff0000, v165
	v_lshlrev_b32_e32 v186, 16, v166
	v_and_b32_e32 v187, 0xffff0000, v166
	v_lshlrev_b32_e32 v188, 16, v167
	v_and_b32_e32 v189, 0xffff0000, v167
	v_mul_f32_e32 v22, v183, v183
	v_fmac_f32_e32 v22, v182, v182
	v_fmac_f32_e32 v22, v184, v184
	v_fmac_f32_e32 v22, v185, v185
	v_mul_f32_e32 v3, v186, v186
	v_add_f32_e32 v22, v3, v22
	v_mul_f32_e32 v3, v187, v187
	v_add_f32_e32 v22, v3, v22
	v_mul_f32_e32 v3, v188, v188
	v_add_f32_e32 v22, v3, v22
	v_mul_f32_e32 v3, v189, v189
	v_add_f32_e32 v22, v3, v22
	v_lshlrev_b32_e32 v182, 16, v168
	v_and_b32_e32 v183, 0xffff0000, v168
	v_lshlrev_b32_e32 v184, 16, v169
	v_and_b32_e32 v185, 0xffff0000, v169
	v_lshlrev_b32_e32 v186, 16, v170
	v_and_b32_e32 v187, 0xffff0000, v170
	v_lshlrev_b32_e32 v188, 16, v171
	v_and_b32_e32 v189, 0xffff0000, v171
	v_mul_f32_e32 v23, v183, v183
	v_fmac_f32_e32 v23, v182, v182
	v_fmac_f32_e32 v23, v184, v184
	v_fmac_f32_e32 v23, v185, v185
	v_mul_f32_e32 v3, v186, v186
	v_add_f32_e32 v23, v3, v23
	v_mul_f32_e32 v3, v187, v187
	v_add_f32_e32 v23, v3, v23
	v_mul_f32_e32 v3, v188, v188
	v_add_f32_e32 v23, v3, v23
	v_mul_f32_e32 v3, v189, v189
	v_add_f32_e32 v23, v3, v23
	ds_bpermute_b32 v24, v4, v20
	ds_bpermute_b32 v25, v4, v21
	ds_bpermute_b32 v26, v4, v22
	ds_bpermute_b32 v27, v4, v23
	s_waitcnt lgkmcnt(3)
	v_add_f32_e32 v20, v20, v24
	s_waitcnt lgkmcnt(2)
	v_add_f32_e32 v21, v21, v25
	s_waitcnt lgkmcnt(1)
	v_add_f32_e32 v22, v22, v26
	s_waitcnt lgkmcnt(0)
	v_add_f32_e32 v23, v23, v27
	ds_bpermute_b32 v24, v5, v20
	ds_bpermute_b32 v25, v5, v21
	ds_bpermute_b32 v26, v5, v22
	ds_bpermute_b32 v27, v5, v23
	s_waitcnt lgkmcnt(3)
	v_add_f32_e32 v20, v20, v24
	s_waitcnt lgkmcnt(2)
	v_add_f32_e32 v21, v21, v25
	s_waitcnt lgkmcnt(1)
	v_add_f32_e32 v22, v22, v26
	s_waitcnt lgkmcnt(0)
	v_add_f32_e32 v23, v23, v27
	ds_bpermute_b32 v24, v6, v20
	ds_bpermute_b32 v25, v6, v21
	ds_bpermute_b32 v26, v6, v22
	ds_bpermute_b32 v27, v6, v23
	s_waitcnt lgkmcnt(3)
	v_add_f32_e32 v20, v20, v24
	s_waitcnt lgkmcnt(2)
	v_add_f32_e32 v21, v21, v25
	s_waitcnt lgkmcnt(1)
	v_add_f32_e32 v22, v22, v26
	s_waitcnt lgkmcnt(0)
	v_add_f32_e32 v23, v23, v27
	ds_bpermute_b32 v24, v7, v20
	ds_bpermute_b32 v25, v7, v21
	ds_bpermute_b32 v26, v7, v22
	ds_bpermute_b32 v27, v7, v23
	s_waitcnt lgkmcnt(3)
	v_add_f32_e32 v20, v20, v24
	s_waitcnt lgkmcnt(2)
	v_add_f32_e32 v21, v21, v25
	s_waitcnt lgkmcnt(1)
	v_add_f32_e32 v22, v22, v26
	s_waitcnt lgkmcnt(0)
	v_add_f32_e32 v23, v23, v27
	ds_bpermute_b32 v24, v8, v20
	ds_bpermute_b32 v25, v8, v21
	ds_bpermute_b32 v26, v8, v22
	ds_bpermute_b32 v27, v8, v23
	s_waitcnt lgkmcnt(3)
	v_add_f32_e32 v20, v20, v24
	s_waitcnt lgkmcnt(2)
	v_add_f32_e32 v21, v21, v25
	s_waitcnt lgkmcnt(1)
	v_add_f32_e32 v22, v22, v26
	s_waitcnt lgkmcnt(0)
	v_add_f32_e32 v23, v23, v27
	ds_bpermute_b32 v24, v9, v20
	ds_bpermute_b32 v25, v9, v21
	ds_bpermute_b32 v26, v9, v22
	ds_bpermute_b32 v27, v9, v23
	s_waitcnt lgkmcnt(3)
	v_add_f32_e32 v20, v20, v24
	s_waitcnt lgkmcnt(2)
	v_add_f32_e32 v21, v21, v25
	s_waitcnt lgkmcnt(1)
	v_add_f32_e32 v22, v22, v26
	s_waitcnt lgkmcnt(0)
	v_add_f32_e32 v23, v23, v27
	v_fmamk_f32 v20, v20, 0x3b000000, v2
	v_fmamk_f32 v21, v21, 0x3b000000, v2
	v_fmamk_f32 v22, v22, 0x3b000000, v2
	v_fmamk_f32 v23, v23, 0x3b000000, v2
	v_rsq_f32_e32 v20, v20
	v_rsq_f32_e32 v21, v21
	v_rsq_f32_e32 v22, v22
	v_rsq_f32_e32 v23, v23
	s_nop 0
	s_waitcnt vmcnt(0)
	v_lshlrev_b32_e32 v182, 16, v156
	v_and_b32_e32 v183, 0xffff0000, v156
	v_lshlrev_b32_e32 v184, 16, v157
	v_and_b32_e32 v185, 0xffff0000, v157
	v_lshlrev_b32_e32 v186, 16, v158
	v_and_b32_e32 v187, 0xffff0000, v158
	v_lshlrev_b32_e32 v188, 16, v159
	v_and_b32_e32 v189, 0xffff0000, v159
	v_mul_f32_e32 v182, v20, v182
	v_mul_f32_e32 v183, v20, v183
	v_mul_f32_e32 v184, v20, v184
	v_mul_f32_e32 v185, v20, v185
	v_mul_f32_e32 v186, v20, v186
	v_mul_f32_e32 v187, v20, v187
	v_mul_f32_e32 v188, v20, v188
	v_mul_f32_e32 v189, v20, v189
	v_mul_f32_e32 v182, v16, v182
	v_mul_f32_e32 v183, v17, v183
	v_mul_f32_e32 v184, v18, v184
	v_mul_f32_e32 v185, v19, v185
	v_mul_f32_e32 v186, v12, v186
	v_mul_f32_e32 v187, v13, v187
	v_mul_f32_e32 v188, v14, v188
	v_mul_f32_e32 v189, v15, v189
	v_cvt_pk_bf16_f32 v190, v182, v183
	v_cvt_pk_bf16_f32 v191, v184, v185
	v_cvt_pk_bf16_f32 v192, v186, v187
	v_cvt_pk_bf16_f32 v193, v188, v189
	global_store_dwordx4 v1, v[190:193], s[40:41]
	v_lshlrev_b32_e32 v182, 16, v160
	v_and_b32_e32 v183, 0xffff0000, v160
	v_lshlrev_b32_e32 v184, 16, v161
	v_and_b32_e32 v185, 0xffff0000, v161
	v_lshlrev_b32_e32 v186, 16, v162
	v_and_b32_e32 v187, 0xffff0000, v162
	v_lshlrev_b32_e32 v188, 16, v163
	v_and_b32_e32 v189, 0xffff0000, v163
	v_mul_f32_e32 v182, v21, v182
	v_mul_f32_e32 v183, v21, v183
	v_mul_f32_e32 v184, v21, v184
	v_mul_f32_e32 v185, v21, v185
	v_mul_f32_e32 v186, v21, v186
	v_mul_f32_e32 v187, v21, v187
	v_mul_f32_e32 v188, v21, v188
	v_mul_f32_e32 v189, v21, v189
	v_mul_f32_e32 v182, v16, v182
	v_mul_f32_e32 v183, v17, v183
	v_mul_f32_e32 v184, v18, v184
	v_mul_f32_e32 v185, v19, v185
	v_mul_f32_e32 v186, v12, v186
	v_mul_f32_e32 v187, v13, v187
	v_mul_f32_e32 v188, v14, v188
	v_mul_f32_e32 v189, v15, v189
	v_cvt_pk_bf16_f32 v190, v182, v183
	v_cvt_pk_bf16_f32 v191, v184, v185
	v_cvt_pk_bf16_f32 v192, v186, v187
	v_cvt_pk_bf16_f32 v193, v188, v189
	global_store_dwordx4 v1, v[190:193], s[40:41] offset:2048
	s_add_u32 s40, s40, 0x1000
	s_addc_u32 s41, s41, 0
	v_lshlrev_b32_e32 v182, 16, v164
	v_and_b32_e32 v183, 0xffff0000, v164
	v_lshlrev_b32_e32 v184, 16, v165
	v_and_b32_e32 v185, 0xffff0000, v165
	v_lshlrev_b32_e32 v186, 16, v166
	v_and_b32_e32 v187, 0xffff0000, v166
	v_lshlrev_b32_e32 v188, 16, v167
	v_and_b32_e32 v189, 0xffff0000, v167
	v_mul_f32_e32 v182, v22, v182
	v_mul_f32_e32 v183, v22, v183
	v_mul_f32_e32 v184, v22, v184
	v_mul_f32_e32 v185, v22, v185
	v_mul_f32_e32 v186, v22, v186
	v_mul_f32_e32 v187, v22, v187
	v_mul_f32_e32 v188, v22, v188
	v_mul_f32_e32 v189, v22, v189
	v_mul_f32_e32 v182, v16, v182
	v_mul_f32_e32 v183, v17, v183
	v_mul_f32_e32 v184, v18, v184
	v_mul_f32_e32 v185, v19, v185
	v_mul_f32_e32 v186, v12, v186
	v_mul_f32_e32 v187, v13, v187
	v_mul_f32_e32 v188, v14, v188
	v_mul_f32_e32 v189, v15, v189
	v_cvt_pk_bf16_f32 v190, v182, v183
	v_cvt_pk_bf16_f32 v191, v184, v185
	v_cvt_pk_bf16_f32 v192, v186, v187
	v_cvt_pk_bf16_f32 v193, v188, v189
	global_store_dwordx4 v1, v[190:193], s[40:41]
	v_lshlrev_b32_e32 v182, 16, v168
	v_and_b32_e32 v183, 0xffff0000, v168
	v_lshlrev_b32_e32 v184, 16, v169
	v_and_b32_e32 v185, 0xffff0000, v169
	v_lshlrev_b32_e32 v186, 16, v170
	v_and_b32_e32 v187, 0xffff0000, v170
	v_lshlrev_b32_e32 v188, 16, v171
	v_and_b32_e32 v189, 0xffff0000, v171
	v_mul_f32_e32 v182, v23, v182
	v_mul_f32_e32 v183, v23, v183
	v_mul_f32_e32 v184, v23, v184
	v_mul_f32_e32 v185, v23, v185
	v_mul_f32_e32 v186, v23, v186
	v_mul_f32_e32 v187, v23, v187
	v_mul_f32_e32 v188, v23, v188
	v_mul_f32_e32 v189, v23, v189
	v_mul_f32_e32 v182, v16, v182
	v_mul_f32_e32 v183, v17, v183
	v_mul_f32_e32 v184, v18, v184
	v_mul_f32_e32 v185, v19, v185
	v_mul_f32_e32 v186, v12, v186
	v_mul_f32_e32 v187, v13, v187
	v_mul_f32_e32 v188, v14, v188
	v_mul_f32_e32 v189, v15, v189
	v_cvt_pk_bf16_f32 v190, v182, v183
	v_cvt_pk_bf16_f32 v191, v184, v185
	v_cvt_pk_bf16_f32 v192, v186, v187
	v_cvt_pk_bf16_f32 v193, v188, v189
	global_store_dwordx4 v1, v[190:193], s[40:41] offset:2048
	s_add_i32 s9, s9, s88
	s_cmpk_gt_i32 s9, 0x2ff
	s_barrier
	s_cbranch_scc0 .LBB0_775
.LBB0_836:
	v_readlane_b32 s0, v241, 9
	v_readlane_b32 s1, v241, 10
	s_andn2_b64 vcc, exec, s[0:1]
	v_readlane_b32 s56, v240, 33
	v_cndmask_b32_e64 v0, 0, 1, s[0:1]
	v_cmp_ne_u32_e64 s[40:41], 1, v0
	s_cbranch_vccnz .LBB0_852
	s_load_dwordx2 s[94:95], s[90:91], 0x108
	s_load_dwordx2 s[96:97], s[90:91], 0xc8
	v_and_b32_e32 v49, 63, v204
	v_lshrrev_b32_e32 v56, 6, v204
	v_and_b32_e32 v51, 7, v204
	v_lshlrev_b32_e32 v50, 2, v49
	v_xor_b32_e32 v57, 0x80, v50
	v_xor_b32_e32 v58, 64, v50
	v_xor_b32_e32 v59, 32, v50
	v_xor_b32_e32 v60, 16, v50
	v_xor_b32_e32 v61, 8, v50
	v_xor_b32_e32 v62, 4, v50
	v_lshrrev_b32_e32 v72, 3, v204
	v_mul_u32_u24_e32 v52, 0x84, v72
	v_lshl_add_u32 v52, v51, 4, v52
	v_mul_u32_u24_e32 v54, 0x420, v49
	v_lshl_add_u32 v54, v56, 4, v54
	v_lshlrev_b32_e32 v55, 14, v56
	v_lshl_add_u32 v55, v49, 4, v55
	v_add_u32_e32 v55, 0x400, v55
	v_mov_b32_e32 v74, 0x358637bd
	s_lshl_b32 s93, s50, 11
	s_waitcnt lgkmcnt(0)
	s_add_u32 s96, s96, s93
	s_addc_u32 s97, s97, 0
	v_lshlrev_b32_e32 v72, 5, v49
	global_load_dwordx4 v[64:67], v72, s[96:97]
	global_load_dwordx4 v[68:71], v72, s[96:97] offset:16
	s_mov_b32 s92, s2
.Lht_item:
	s_cmp_lt_u32 s92, 0x80
	s_cbranch_scc0 .Lht_lat
	s_lshr_b32 s93, s92, 2
	s_mul_i32 s98, s93, 0xc0000
	s_and_b32 s93, s92, 3
	s_lshl_b32 s93, s93, 7
	s_add_u32 s98, s98, s93
	s_add_u32 s98, s98, 0x81b2000
	s_add_u32 s72, s94, s98
	s_addc_u32 s73, s95, 0
	s_movk_i32 s74, 0x200
	s_branch .Lht_go
.Lht_lat:
	s_sub_u32 s93, s92, 0x80
	s_lshr_b32 s99, s93, 6
	s_mul_i32 s98, s99, 0xc00000
	s_and_b32 s93, s93, 63
	s_lshl_b32 s93, s93, 7
	s_add_u32 s98, s98, s93
	s_add_u32 s98, s98, 0x99b2000
	s_add_u32 s72, s94, s98
	s_addc_u32 s73, s95, 0
	s_movk_i32 s74, 0x2000
.Lht_go:
	v_lshrrev_b32_e32 v72, 3, v204
	v_mul_lo_u32 v53, v72, s74
	v_lshl_add_u32 v53, v51, 4, v53
	s_lshl_b32 s93, s74, 6
	global_load_dwordx4 v[214:217], v53, s[72:73] nt
	v_add_u32_e32 v53, s93, v53
	global_load_dwordx4 v[218:221], v53, s[72:73] nt
	v_add_u32_e32 v53, s93, v53
	global_load_dwordx4 v[222:225], v53, s[72:73] nt
	v_add_u32_e32 v53, s93, v53
	global_load_dwordx4 v[226:229], v53, s[72:73] nt
	v_add_u32_e32 v53, s93, v53
	global_load_dwordx4 v[230:233], v53, s[72:73] nt
	v_add_u32_e32 v53, s93, v53
	global_load_dwordx4 v[234:237], v53, s[72:73] nt
	v_add_u32_e32 v53, s93, v53
	global_load_dwordx4 v[198:201], v53, s[72:73] nt
	v_add_u32_e32 v53, s93, v53
	global_load_dwordx4 v[182:185], v53, s[72:73] nt
	s_lshl_b32 s98, s92, 17
	s_add_u32 s98, s98, 0x21b2000
	s_add_u32 s98, s94, s98
	s_addc_u32 s99, s95, 0
	v_mov_b32_e32 v73, v52
	s_waitcnt vmcnt(7)
	ds_write2_b32 v73, v214, v215 offset1:1
	ds_write2_b32 v73, v216, v217 offset0:2 offset1:3
	v_add_u32_e32 v73, 0x2100, v73
	s_waitcnt vmcnt(6)
	ds_write2_b32 v73, v218, v219 offset1:1
	ds_write2_b32 v73, v220, v221 offset0:2 offset1:3
	v_add_u32_e32 v73, 0x2100, v73
	s_waitcnt vmcnt(5)
	ds_write2_b32 v73, v222, v223 offset1:1
	ds_write2_b32 v73, v224, v225 offset0:2 offset1:3
	v_add_u32_e32 v73, 0x2100, v73
	s_waitcnt vmcnt(4)
	ds_write2_b32 v73, v226, v227 offset1:1
	ds_write2_b32 v73, v228, v229 offset0:2 offset1:3
	v_add_u32_e32 v73, 0x2100, v73
	s_waitcnt vmcnt(3)
	ds_write2_b32 v73, v230, v231 offset1:1
	ds_write2_b32 v73, v232, v233 offset0:2 offset1:3
	v_add_u32_e32 v73, 0x2100, v73
	s_waitcnt vmcnt(2)
	ds_write2_b32 v73, v234, v235 offset1:1
	ds_write2_b32 v73, v236, v237 offset0:2 offset1:3
	v_add_u32_e32 v73, 0x2100, v73
	s_waitcnt vmcnt(1)
	ds_write2_b32 v73, v198, v199 offset1:1
	ds_write2_b32 v73, v200, v201 offset0:2 offset1:3
	v_add_u32_e32 v73, 0x2100, v73
	s_waitcnt vmcnt(0)
	ds_write2_b32 v73, v182, v183 offset1:1
	ds_write2_b32 v73, v184, v185 offset0:2 offset1:3
	s_waitcnt lgkmcnt(0)
	s_barrier
	ds_read_u16 v214, v54 offset:0
	ds_read_u16 v215, v54 offset:132
	ds_read_u16 v216, v54 offset:264
	ds_read_u16 v217, v54 offset:396
	ds_read_u16 v218, v54 offset:528
	ds_read_u16 v219, v54 offset:660
	ds_read_u16 v220, v54 offset:792
	ds_read_u16 v221, v54 offset:924
	ds_read_u16 v222, v54 offset:2
	ds_read_u16 v223, v54 offset:134
	ds_read_u16 v224, v54 offset:266
	ds_read_u16 v225, v54 offset:398
	ds_read_u16 v226, v54 offset:530
	ds_read_u16 v227, v54 offset:662
	ds_read_u16 v228, v54 offset:794
	ds_read_u16 v229, v54 offset:926
	ds_read_u16 v230, v54 offset:4
	ds_read_u16 v231, v54 offset:136
	ds_read_u16 v232, v54 offset:268
	ds_read_u16 v233, v54 offset:400
	ds_read_u16 v234, v54 offset:532
	ds_read_u16 v235, v54 offset:664
	ds_read_u16 v236, v54 offset:796
	ds_read_u16 v237, v54 offset:928
	ds_read_u16 v198, v54 offset:6
	ds_read_u16 v199, v54 offset:138
	ds_read_u16 v200, v54 offset:270
	ds_read_u16 v201, v54 offset:402
	ds_read_u16 v182, v54 offset:534
	ds_read_u16 v183, v54 offset:666
	ds_read_u16 v184, v54 offset:798
	ds_read_u16 v185, v54 offset:930
	s_waitcnt lgkmcnt(15)
	v_lshlrev_b32_e32 v214, 16, v214
	v_lshlrev_b32_e32 v215, 16, v215
	v_lshlrev_b32_e32 v216, 16, v216
	v_lshlrev_b32_e32 v217, 16, v217
	v_lshlrev_b32_e32 v218, 16, v218
	v_lshlrev_b32_e32 v219, 16, v219
	v_lshlrev_b32_e32 v220, 16, v220
	v_lshlrev_b32_e32 v221, 16, v221
	v_mul_f32_e32 v156, v215, v215
	v_fmac_f32_e32 v156, v214, v214
	v_fmac_f32_e32 v156, v216, v216
	v_fmac_f32_e32 v156, v217, v217
	v_mul_f32_e32 v75, v218, v218
	v_add_f32_e32 v156, v156, v75
	v_mul_f32_e32 v75, v219, v219
	v_add_f32_e32 v156, v156, v75
	v_mul_f32_e32 v75, v220, v220
	v_add_f32_e32 v156, v156, v75
	v_mul_f32_e32 v75, v221, v221
	v_add_f32_e32 v156, v156, v75
	s_waitcnt lgkmcnt(15)
	v_lshlrev_b32_e32 v222, 16, v222
	v_lshlrev_b32_e32 v223, 16, v223
	v_lshlrev_b32_e32 v224, 16, v224
	v_lshlrev_b32_e32 v225, 16, v225
	v_lshlrev_b32_e32 v226, 16, v226
	v_lshlrev_b32_e32 v227, 16, v227
	v_lshlrev_b32_e32 v228, 16, v228
	v_lshlrev_b32_e32 v229, 16, v229
	v_mul_f32_e32 v157, v223, v223
	v_fmac_f32_e32 v157, v222, v222
	v_fmac_f32_e32 v157, v224, v224
	v_fmac_f32_e32 v157, v225, v225
	v_mul_f32_e32 v75, v226, v226
	v_add_f32_e32 v157, v157, v75
	v_mul_f32_e32 v75, v227, v227
	v_add_f32_e32 v157, v157, v75
	v_mul_f32_e32 v75, v228, v228
	v_add_f32_e32 v157, v157, v75
	v_mul_f32_e32 v75, v229, v229
	v_add_f32_e32 v157, v157, v75
	s_waitcnt lgkmcnt(8)
	v_lshlrev_b32_e32 v230, 16, v230
	v_lshlrev_b32_e32 v231, 16, v231
	v_lshlrev_b32_e32 v232, 16, v232
	v_lshlrev_b32_e32 v233, 16, v233
	v_lshlrev_b32_e32 v234, 16, v234
	v_lshlrev_b32_e32 v235, 16, v235
	v_lshlrev_b32_e32 v236, 16, v236
	v_lshlrev_b32_e32 v237, 16, v237
	v_mul_f32_e32 v158, v231, v231
	v_fmac_f32_e32 v158, v230, v230
	v_fmac_f32_e32 v158, v232, v232
	v_fmac_f32_e32 v158, v233, v233
	v_mul_f32_e32 v75, v234, v234
	v_add_f32_e32 v158, v158, v75
	v_mul_f32_e32 v75, v235, v235
	v_add_f32_e32 v158, v158, v75
	v_mul_f32_e32 v75, v236, v236
	v_add_f32_e32 v158, v158, v75
	v_mul_f32_e32 v75, v237, v237
	v_add_f32_e32 v158, v158, v75
	s_waitcnt lgkmcnt(0)
	v_lshlrev_b32_e32 v198, 16, v198
	v_lshlrev_b32_e32 v199, 16, v199
	v_lshlrev_b32_e32 v200, 16, v200
	v_lshlrev_b32_e32 v201, 16, v201
	v_lshlrev_b32_e32 v182, 16, v182
	v_lshlrev_b32_e32 v183, 16, v183
	v_lshlrev_b32_e32 v184, 16, v184
	v_lshlrev_b32_e32 v185, 16, v185
	v_mul_f32_e32 v159, v199, v199
	v_fmac_f32_e32 v159, v198, v198
	v_fmac_f32_e32 v159, v200, v200
	v_fmac_f32_e32 v159, v201, v201
	v_mul_f32_e32 v75, v182, v182
	v_add_f32_e32 v159, v159, v75
	v_mul_f32_e32 v75, v183, v183
	v_add_f32_e32 v159, v159, v75
	v_mul_f32_e32 v75, v184, v184
	v_add_f32_e32 v159, v159, v75
	v_mul_f32_e32 v75, v185, v185
	v_add_f32_e32 v159, v159, v75
	ds_bpermute_b32 v164, v57, v156
	ds_bpermute_b32 v165, v57, v157
	ds_bpermute_b32 v166, v57, v158
	ds_bpermute_b32 v167, v57, v159
	s_waitcnt lgkmcnt(3)
	v_add_f32_e32 v156, v156, v164
	s_waitcnt lgkmcnt(2)
	v_add_f32_e32 v157, v157, v165
	s_waitcnt lgkmcnt(1)
	v_add_f32_e32 v158, v158, v166
	s_waitcnt lgkmcnt(0)
	v_add_f32_e32 v159, v159, v167
	ds_bpermute_b32 v164, v58, v156
	ds_bpermute_b32 v165, v58, v157
	ds_bpermute_b32 v166, v58, v158
	ds_bpermute_b32 v167, v58, v159
	s_waitcnt lgkmcnt(3)
	v_add_f32_e32 v156, v156, v164
	s_waitcnt lgkmcnt(2)
	v_add_f32_e32 v157, v157, v165
	s_waitcnt lgkmcnt(1)
	v_add_f32_e32 v158, v158, v166
	s_waitcnt lgkmcnt(0)
	v_add_f32_e32 v159, v159, v167
	ds_bpermute_b32 v164, v59, v156
	ds_bpermute_b32 v165, v59, v157
	ds_bpermute_b32 v166, v59, v158
	ds_bpermute_b32 v167, v59, v159
	s_waitcnt lgkmcnt(3)
	v_add_f32_e32 v156, v156, v164
	s_waitcnt lgkmcnt(2)
	v_add_f32_e32 v157, v157, v165
	s_waitcnt lgkmcnt(1)
	v_add_f32_e32 v158, v158, v166
	s_waitcnt lgkmcnt(0)
	v_add_f32_e32 v159, v159, v167
	ds_bpermute_b32 v164, v60, v156
	ds_bpermute_b32 v165, v60, v157
	ds_bpermute_b32 v166, v60, v158
	ds_bpermute_b32 v167, v60, v159
	s_waitcnt lgkmcnt(3)
	v_add_f32_e32 v156, v156, v164
	s_waitcnt lgkmcnt(2)
	v_add_f32_e32 v157, v157, v165
	s_waitcnt lgkmcnt(1)
	v_add_f32_e32 v158, v158, v166
	s_waitcnt lgkmcnt(0)
	v_add_f32_e32 v159, v159, v167
	ds_bpermute_b32 v164, v61, v156
	ds_bpermute_b32 v165, v61, v157
	ds_bpermute_b32 v166, v61, v158
	ds_bpermute_b32 v167, v61, v159
	s_waitcnt lgkmcnt(3)
	v_add_f32_e32 v156, v156, v164
	s_waitcnt lgkmcnt(2)
	v_add_f32_e32 v157, v157, v165
	s_waitcnt lgkmcnt(1)
	v_add_f32_e32 v158, v158, v166
	s_waitcnt lgkmcnt(0)
	v_add_f32_e32 v159, v159, v167
	ds_bpermute_b32 v164, v62, v156
	ds_bpermute_b32 v165, v62, v157
	ds_bpermute_b32 v166, v62, v158
	ds_bpermute_b32 v167, v62, v159
	s_waitcnt lgkmcnt(3)
	v_add_f32_e32 v156, v156, v164
	s_waitcnt lgkmcnt(2)
	v_add_f32_e32 v157, v157, v165
	s_waitcnt lgkmcnt(1)
	v_add_f32_e32 v158, v158, v166
	s_waitcnt lgkmcnt(0)
	v_add_f32_e32 v159, v159, v167
	v_fmamk_f32 v156, v156, 0x3b000000, v74
	v_fmamk_f32 v157, v157, 0x3b000000, v74
	v_fmamk_f32 v158, v158, 0x3b000000, v74
	v_fmamk_f32 v159, v159, 0x3b000000, v74
	v_rsq_f32_e32 v156, v156
	v_rsq_f32_e32 v157, v157
	v_rsq_f32_e32 v158, v158
	v_rsq_f32_e32 v159, v159
	s_nop 0
	s_waitcnt vmcnt(0)
	v_mul_f32_e32 v186, v156, v214
	v_mul_f32_e32 v187, v156, v215
	v_mul_f32_e32 v188, v156, v216
	v_mul_f32_e32 v189, v156, v217
	v_mul_f32_e32 v190, v156, v218
	v_mul_f32_e32 v191, v156, v219
	v_mul_f32_e32 v192, v156, v220
	v_mul_f32_e32 v193, v156, v221
	v_mul_f32_e32 v186, v64, v186
	v_mul_f32_e32 v187, v65, v187
	v_mul_f32_e32 v188, v66, v188
	v_mul_f32_e32 v189, v67, v189
	v_mul_f32_e32 v190, v68, v190
	v_mul_f32_e32 v191, v69, v191
	v_mul_f32_e32 v192, v70, v192
	v_mul_f32_e32 v193, v71, v193
	v_cvt_pk_bf16_f32 v194, v186, v187
	v_cvt_pk_bf16_f32 v195, v188, v189
	v_cvt_pk_bf16_f32 v196, v190, v191
	v_cvt_pk_bf16_f32 v197, v192, v193
	global_store_dwordx4 v55, v[194:197], s[98:99]
	v_mul_f32_e32 v186, v157, v222
	v_mul_f32_e32 v187, v157, v223
	v_mul_f32_e32 v188, v157, v224
	v_mul_f32_e32 v189, v157, v225
	v_mul_f32_e32 v190, v157, v226
	v_mul_f32_e32 v191, v157, v227
	v_mul_f32_e32 v192, v157, v228
	v_mul_f32_e32 v193, v157, v229
	v_mul_f32_e32 v186, v64, v186
	v_mul_f32_e32 v187, v65, v187
	v_mul_f32_e32 v188, v66, v188
	v_mul_f32_e32 v189, v67, v189
	v_mul_f32_e32 v190, v68, v190
	v_mul_f32_e32 v191, v69, v191
	v_mul_f32_e32 v192, v70, v192
	v_mul_f32_e32 v193, v71, v193
	v_cvt_pk_bf16_f32 v194, v186, v187
	v_cvt_pk_bf16_f32 v195, v188, v189
	v_cvt_pk_bf16_f32 v196, v190, v191
	v_cvt_pk_bf16_f32 v197, v192, v193
	global_store_dwordx4 v55, v[194:197], s[98:99] offset:2048
	s_add_u32 s98, s98, 0x1000
	s_addc_u32 s99, s99, 0
	v_mul_f32_e32 v186, v158, v230
	v_mul_f32_e32 v187, v158, v231
	v_mul_f32_e32 v188, v158, v232
	v_mul_f32_e32 v189, v158, v233
	v_mul_f32_e32 v190, v158, v234
	v_mul_f32_e32 v191, v158, v235
	v_mul_f32_e32 v192, v158, v236
	v_mul_f32_e32 v193, v158, v237
	v_mul_f32_e32 v186, v64, v186
	v_mul_f32_e32 v187, v65, v187
	v_mul_f32_e32 v188, v66, v188
	v_mul_f32_e32 v189, v67, v189
	v_mul_f32_e32 v190, v68, v190
	v_mul_f32_e32 v191, v69, v191
	v_mul_f32_e32 v192, v70, v192
	v_mul_f32_e32 v193, v71, v193
	v_cvt_pk_bf16_f32 v194, v186, v187
	v_cvt_pk_bf16_f32 v195, v188, v189
	v_cvt_pk_bf16_f32 v196, v190, v191
	v_cvt_pk_bf16_f32 v197, v192, v193
	global_store_dwordx4 v55, v[194:197], s[98:99]
	v_mul_f32_e32 v186, v159, v198
	v_mul_f32_e32 v187, v159, v199
	v_mul_f32_e32 v188, v159, v200
	v_mul_f32_e32 v189, v159, v201
	v_mul_f32_e32 v190, v159, v182
	v_mul_f32_e32 v191, v159, v183
	v_mul_f32_e32 v192, v159, v184
	v_mul_f32_e32 v193, v159, v185
	v_mul_f32_e32 v186, v64, v186
	v_mul_f32_e32 v187, v65, v187
	v_mul_f32_e32 v188, v66, v188
	v_mul_f32_e32 v189, v67, v189
	v_mul_f32_e32 v190, v68, v190
	v_mul_f32_e32 v191, v69, v191
	v_mul_f32_e32 v192, v70, v192
	v_mul_f32_e32 v193, v71, v193
	v_cvt_pk_bf16_f32 v194, v186, v187
	v_cvt_pk_bf16_f32 v195, v188, v189
	v_cvt_pk_bf16_f32 v196, v190, v191
	v_cvt_pk_bf16_f32 v197, v192, v193
	global_store_dwordx4 v55, v[194:197], s[98:99] offset:2048
	s_add_u32 s98, s98, 0x1000
	s_addc_u32 s99, s99, 0
	ds_read_u16 v214, v54 offset:8
	ds_read_u16 v215, v54 offset:140
	ds_read_u16 v216, v54 offset:272
	ds_read_u16 v217, v54 offset:404
	ds_read_u16 v218, v54 offset:536
	ds_read_u16 v219, v54 offset:668
	ds_read_u16 v220, v54 offset:800
	ds_read_u16 v221, v54 offset:932
	ds_read_u16 v222, v54 offset:10
	ds_read_u16 v223, v54 offset:142
	ds_read_u16 v224, v54 offset:274
	ds_read_u16 v225, v54 offset:406
	ds_read_u16 v226, v54 offset:538
	ds_read_u16 v227, v54 offset:670
	ds_read_u16 v228, v54 offset:802
	ds_read_u16 v229, v54 offset:934
	ds_read_u16 v230, v54 offset:12
	ds_read_u16 v231, v54 offset:144
	ds_read_u16 v232, v54 offset:276
	ds_read_u16 v233, v54 offset:408
	ds_read_u16 v234, v54 offset:540
	ds_read_u16 v235, v54 offset:672
	ds_read_u16 v236, v54 offset:804
	ds_read_u16 v237, v54 offset:936
	ds_read_u16 v198, v54 offset:14
	ds_read_u16 v199, v54 offset:146
	ds_read_u16 v200, v54 offset:278
	ds_read_u16 v201, v54 offset:410
	ds_read_u16 v182, v54 offset:542
	ds_read_u16 v183, v54 offset:674
	ds_read_u16 v184, v54 offset:806
	ds_read_u16 v185, v54 offset:938
	s_waitcnt lgkmcnt(15)
	v_lshlrev_b32_e32 v214, 16, v214
	v_lshlrev_b32_e32 v215, 16, v215
	v_lshlrev_b32_e32 v216, 16, v216
	v_lshlrev_b32_e32 v217, 16, v217
	v_lshlrev_b32_e32 v218, 16, v218
	v_lshlrev_b32_e32 v219, 16, v219
	v_lshlrev_b32_e32 v220, 16, v220
	v_lshlrev_b32_e32 v221, 16, v221
	v_mul_f32_e32 v160, v215, v215
	v_fmac_f32_e32 v160, v214, v214
	v_fmac_f32_e32 v160, v216, v216
	v_fmac_f32_e32 v160, v217, v217
	v_mul_f32_e32 v75, v218, v218
	v_add_f32_e32 v160, v160, v75
	v_mul_f32_e32 v75, v219, v219
	v_add_f32_e32 v160, v160, v75
	v_mul_f32_e32 v75, v220, v220
	v_add_f32_e32 v160, v160, v75
	v_mul_f32_e32 v75, v221, v221
	v_add_f32_e32 v160, v160, v75
	s_waitcnt lgkmcnt(15)
	v_lshlrev_b32_e32 v222, 16, v222
	v_lshlrev_b32_e32 v223, 16, v223
	v_lshlrev_b32_e32 v224, 16, v224
	v_lshlrev_b32_e32 v225, 16, v225
	v_lshlrev_b32_e32 v226, 16, v226
	v_lshlrev_b32_e32 v227, 16, v227
	v_lshlrev_b32_e32 v228, 16, v228
	v_lshlrev_b32_e32 v229, 16, v229
	v_mul_f32_e32 v161, v223, v223
	v_fmac_f32_e32 v161, v222, v222
	v_fmac_f32_e32 v161, v224, v224
	v_fmac_f32_e32 v161, v225, v225
	v_mul_f32_e32 v75, v226, v226
	v_add_f32_e32 v161, v161, v75
	v_mul_f32_e32 v75, v227, v227
	v_add_f32_e32 v161, v161, v75
	v_mul_f32_e32 v75, v228, v228
	v_add_f32_e32 v161, v161, v75
	v_mul_f32_e32 v75, v229, v229
	v_add_f32_e32 v161, v161, v75
	s_waitcnt lgkmcnt(8)
	v_lshlrev_b32_e32 v230, 16, v230
	v_lshlrev_b32_e32 v231, 16, v231
	v_lshlrev_b32_e32 v232, 16, v232
	v_lshlrev_b32_e32 v233, 16, v233
	v_lshlrev_b32_e32 v234, 16, v234
	v_lshlrev_b32_e32 v235, 16, v235
	v_lshlrev_b32_e32 v236, 16, v236
	v_lshlrev_b32_e32 v237, 16, v237
	v_mul_f32_e32 v162, v231, v231
	v_fmac_f32_e32 v162, v230, v230
	v_fmac_f32_e32 v162, v232, v232
	v_fmac_f32_e32 v162, v233, v233
	v_mul_f32_e32 v75, v234, v234
	v_add_f32_e32 v162, v162, v75
	v_mul_f32_e32 v75, v235, v235
	v_add_f32_e32 v162, v162, v75
	v_mul_f32_e32 v75, v236, v236
	v_add_f32_e32 v162, v162, v75
	v_mul_f32_e32 v75, v237, v237
	v_add_f32_e32 v162, v162, v75
	s_waitcnt lgkmcnt(0)
	v_lshlrev_b32_e32 v198, 16, v198
	v_lshlrev_b32_e32 v199, 16, v199
	v_lshlrev_b32_e32 v200, 16, v200
	v_lshlrev_b32_e32 v201, 16, v201
	v_lshlrev_b32_e32 v182, 16, v182
	v_lshlrev_b32_e32 v183, 16, v183
	v_lshlrev_b32_e32 v184, 16, v184
	v_lshlrev_b32_e32 v185, 16, v185
	v_mul_f32_e32 v163, v199, v199
	v_fmac_f32_e32 v163, v198, v198
	v_fmac_f32_e32 v163, v200, v200
	v_fmac_f32_e32 v163, v201, v201
	v_mul_f32_e32 v75, v182, v182
	v_add_f32_e32 v163, v163, v75
	v_mul_f32_e32 v75, v183, v183
	v_add_f32_e32 v163, v163, v75
	v_mul_f32_e32 v75, v184, v184
	v_add_f32_e32 v163, v163, v75
	v_mul_f32_e32 v75, v185, v185
	v_add_f32_e32 v163, v163, v75
	ds_bpermute_b32 v168, v57, v160
	ds_bpermute_b32 v169, v57, v161
	ds_bpermute_b32 v170, v57, v162
	ds_bpermute_b32 v171, v57, v163
	s_waitcnt lgkmcnt(3)
	v_add_f32_e32 v160, v160, v168
	s_waitcnt lgkmcnt(2)
	v_add_f32_e32 v161, v161, v169
	s_waitcnt lgkmcnt(1)
	v_add_f32_e32 v162, v162, v170
	s_waitcnt lgkmcnt(0)
	v_add_f32_e32 v163, v163, v171
	ds_bpermute_b32 v168, v58, v160
	ds_bpermute_b32 v169, v58, v161
	ds_bpermute_b32 v170, v58, v162
	ds_bpermute_b32 v171, v58, v163
	s_waitcnt lgkmcnt(3)
	v_add_f32_e32 v160, v160, v168
	s_waitcnt lgkmcnt(2)
	v_add_f32_e32 v161, v161, v169
	s_waitcnt lgkmcnt(1)
	v_add_f32_e32 v162, v162, v170
	s_waitcnt lgkmcnt(0)
	v_add_f32_e32 v163, v163, v171
	ds_bpermute_b32 v168, v59, v160
	ds_bpermute_b32 v169, v59, v161
	ds_bpermute_b32 v170, v59, v162
	ds_bpermute_b32 v171, v59, v163
	s_waitcnt lgkmcnt(3)
	v_add_f32_e32 v160, v160, v168
	s_waitcnt lgkmcnt(2)
	v_add_f32_e32 v161, v161, v169
	s_waitcnt lgkmcnt(1)
	v_add_f32_e32 v162, v162, v170
	s_waitcnt lgkmcnt(0)
	v_add_f32_e32 v163, v163, v171
	ds_bpermute_b32 v168, v60, v160
	ds_bpermute_b32 v169, v60, v161
	ds_bpermute_b32 v170, v60, v162
	ds_bpermute_b32 v171, v60, v163
	s_waitcnt lgkmcnt(3)
	v_add_f32_e32 v160, v160, v168
	s_waitcnt lgkmcnt(2)
	v_add_f32_e32 v161, v161, v169
	s_waitcnt lgkmcnt(1)
	v_add_f32_e32 v162, v162, v170
	s_waitcnt lgkmcnt(0)
	v_add_f32_e32 v163, v163, v171
	ds_bpermute_b32 v168, v61, v160
	ds_bpermute_b32 v169, v61, v161
	ds_bpermute_b32 v170, v61, v162
	ds_bpermute_b32 v171, v61, v163
	s_waitcnt lgkmcnt(3)
	v_add_f32_e32 v160, v160, v168
	s_waitcnt lgkmcnt(2)
	v_add_f32_e32 v161, v161, v169
	s_waitcnt lgkmcnt(1)
	v_add_f32_e32 v162, v162, v170
	s_waitcnt lgkmcnt(0)
	v_add_f32_e32 v163, v163, v171
	ds_bpermute_b32 v168, v62, v160
	ds_bpermute_b32 v169, v62, v161
	ds_bpermute_b32 v170, v62, v162
	ds_bpermute_b32 v171, v62, v163
	s_waitcnt lgkmcnt(3)
	v_add_f32_e32 v160, v160, v168
	s_waitcnt lgkmcnt(2)
	v_add_f32_e32 v161, v161, v169
	s_waitcnt lgkmcnt(1)
	v_add_f32_e32 v162, v162, v170
	s_waitcnt lgkmcnt(0)
	v_add_f32_e32 v163, v163, v171
	v_fmamk_f32 v160, v160, 0x3b000000, v74
	v_fmamk_f32 v161, v161, 0x3b000000, v74
	v_fmamk_f32 v162, v162, 0x3b000000, v74
	v_fmamk_f32 v163, v163, 0x3b000000, v74
	v_rsq_f32_e32 v160, v160
	v_rsq_f32_e32 v161, v161
	v_rsq_f32_e32 v162, v162
	v_rsq_f32_e32 v163, v163
	s_nop 0
	v_mul_f32_e32 v186, v160, v214
	v_mul_f32_e32 v187, v160, v215
	v_mul_f32_e32 v188, v160, v216
	v_mul_f32_e32 v189, v160, v217
	v_mul_f32_e32 v190, v160, v218
	v_mul_f32_e32 v191, v160, v219
	v_mul_f32_e32 v192, v160, v220
	v_mul_f32_e32 v193, v160, v221
	v_mul_f32_e32 v186, v64, v186
	v_mul_f32_e32 v187, v65, v187
	v_mul_f32_e32 v188, v66, v188
	v_mul_f32_e32 v189, v67, v189
	v_mul_f32_e32 v190, v68, v190
	v_mul_f32_e32 v191, v69, v191
	v_mul_f32_e32 v192, v70, v192
	v_mul_f32_e32 v193, v71, v193
	v_cvt_pk_bf16_f32 v194, v186, v187
	v_cvt_pk_bf16_f32 v195, v188, v189
	v_cvt_pk_bf16_f32 v196, v190, v191
	v_cvt_pk_bf16_f32 v197, v192, v193
	global_store_dwordx4 v55, v[194:197], s[98:99]
	v_mul_f32_e32 v186, v161, v222
	v_mul_f32_e32 v187, v161, v223
	v_mul_f32_e32 v188, v161, v224
	v_mul_f32_e32 v189, v161, v225
	v_mul_f32_e32 v190, v161, v226
	v_mul_f32_e32 v191, v161, v227
	v_mul_f32_e32 v192, v161, v228
	v_mul_f32_e32 v193, v161, v229
	v_mul_f32_e32 v186, v64, v186
	v_mul_f32_e32 v187, v65, v187
	v_mul_f32_e32 v188, v66, v188
	v_mul_f32_e32 v189, v67, v189
	v_mul_f32_e32 v190, v68, v190
	v_mul_f32_e32 v191, v69, v191
	v_mul_f32_e32 v192, v70, v192
	v_mul_f32_e32 v193, v71, v193
	v_cvt_pk_bf16_f32 v194, v186, v187
	v_cvt_pk_bf16_f32 v195, v188, v189
	v_cvt_pk_bf16_f32 v196, v190, v191
	v_cvt_pk_bf16_f32 v197, v192, v193
	global_store_dwordx4 v55, v[194:197], s[98:99] offset:2048
	s_add_u32 s98, s98, 0x1000
	s_addc_u32 s99, s99, 0
	v_mul_f32_e32 v186, v162, v230
	v_mul_f32_e32 v187, v162, v231
	v_mul_f32_e32 v188, v162, v232
	v_mul_f32_e32 v189, v162, v233
	v_mul_f32_e32 v190, v162, v234
	v_mul_f32_e32 v191, v162, v235
	v_mul_f32_e32 v192, v162, v236
	v_mul_f32_e32 v193, v162, v237
	v_mul_f32_e32 v186, v64, v186
	v_mul_f32_e32 v187, v65, v187
	v_mul_f32_e32 v188, v66, v188
	v_mul_f32_e32 v189, v67, v189
	v_mul_f32_e32 v190, v68, v190
	v_mul_f32_e32 v191, v69, v191
	v_mul_f32_e32 v192, v70, v192
	v_mul_f32_e32 v193, v71, v193
	v_cvt_pk_bf16_f32 v194, v186, v187
	v_cvt_pk_bf16_f32 v195, v188, v189
	v_cvt_pk_bf16_f32 v196, v190, v191
	v_cvt_pk_bf16_f32 v197, v192, v193
	global_store_dwordx4 v55, v[194:197], s[98:99]
	v_mul_f32_e32 v186, v163, v198
	v_mul_f32_e32 v187, v163, v199
	v_mul_f32_e32 v188, v163, v200
	v_mul_f32_e32 v189, v163, v201
	v_mul_f32_e32 v190, v163, v182
	v_mul_f32_e32 v191, v163, v183
	v_mul_f32_e32 v192, v163, v184
	v_mul_f32_e32 v193, v163, v185
	v_mul_f32_e32 v186, v64, v186
	v_mul_f32_e32 v187, v65, v187
	v_mul_f32_e32 v188, v66, v188
	v_mul_f32_e32 v189, v67, v189
	v_mul_f32_e32 v190, v68, v190
	v_mul_f32_e32 v191, v69, v191
	v_mul_f32_e32 v192, v70, v192
	v_mul_f32_e32 v193, v71, v193
	v_cvt_pk_bf16_f32 v194, v186, v187
	v_cvt_pk_bf16_f32 v195, v188, v189
	v_cvt_pk_bf16_f32 v196, v190, v191
	v_cvt_pk_bf16_f32 v197, v192, v193
	global_store_dwordx4 v55, v[194:197], s[98:99] offset:2048
	s_add_u32 s92, s92, s88
	s_cmp_lt_u32 s92, 0x180
	s_barrier
	s_cbranch_scc1 .Lht_item
